# instruction selection: DSA selection mask applied through a 16-entry LDS table (4 ds_read_b128 + 8 v_pk_add per 32-key step instead of 32 bit ops); second exchange barrier dropped in the re-aligned od
# baseline (speedup 1.0000x reference)
; #define LAS __attribute__((address_space(3)))
;     __device__ __forceinline__ void operator()(const f32x4 (&acc_c)[2][2][4][2], const Unit& u, int wr, int wc, int fr, int fq) const {
;     ...
;             asm volatile("s_waitcnt lgkmcnt(0)" ::: "memory");
;             __builtin_amdgcn_s_barrier(); __builtin_amdgcn_s_barrier();
;             asm volatile("" ::: "memory");
; #pragma unroll
;             for (int ai = 0; ai < 2; ++ai)
; #pragma unroll
;                 for (int m = 0; m < 4; ++m)
; #pragma unroll
;                     for (int bj = 0; bj < 2; ++bj) { const int kind = bj ? kind1 : kind0;
;                         if (kind != 0) {
;                             const f32x4 pp = *(const LAS f32x4*)(xch + ((ai * HALF + wr * 64 + m * 16 + fr) * 2 + bj) * 4);
;                             const float sum = kind == 1 ? ((wc & 2) ? (pp[2] + pp[3]) : (pp[0] + pp[1])) : ((pp[0] + pp[1]) + (pp[2] + pp[3]));
.LBB0_180:
	s_or_b64 exec, exec, s[14:15]
	s_waitcnt lgkmcnt(0)
	s_barrier
	s_waitcnt lgkmcnt(0)
	ds_read_b128 v[10:13], v164
	s_andn2_b64 vcc, exec, s[44:45]
	s_mov_b64 s[14:15], -1
	s_cbranch_vccnz .LBB0_187
	s_andn2_b64 vcc, exec, s[34:35]
	s_cbranch_vccnz .LBB0_183
	s_waitcnt lgkmcnt(0)
	v_add_f32_e32 v141, v12, v13
	s_mov_b64 s[14:15], 0

; #define LAS __attribute__((address_space(3)))
; __device__ __forceinline__ void dsa_attn_item(CParams& p, LAS unsigned char* lds, int b, int qb, int tid_in, int wave) {
;     ...
;     const int hd = wave & 3, qs = wave >> 2, r = lane & 31, hh = lane >> 5;
;     const int tb0 = b * SEQ; const int q0 = qb * 64 + 32 * qs;
;     for (int i = tid; i < 4 * 132; i += NTHREADS) bdl[i] = bd[i];
;     h16x8 qf[8];
; #pragma unroll
;     for (int s = 0; s < 8; ++s) qf[s] = *(const h16x8*)(proj + (size_t)(tb0 + q0 + r) * OD_N + 1536 + hd * 128 + 16 * s + 8 * hh);
;     f32x16 o[4];
; #pragma unroll
;     for (int d = 0; d < 4; ++d)
; #pragma unroll
;         for (int i = 0; i < 16; ++i) o[d][i] = 0.f;
;     float m_run = -INFINITY, l_run = 0.f;
;     const int qp = q0 + r;
;     const int vlo = r * 72 + ((hh ^ (r >> 3)) << 2), vhi = r * 72 + (((hh ^ (r >> 3)) ^ 2) << 2);
;     const unsigned long long* bmq = bm + (size_t)(tb0 + qp) * 64;
;     const LAS float* bdh = bdl + hd * 132;
;     const int nkt = qb + 1;
;     h16x8 pk[2], pv[2];
; #pragma unroll
;     for (int i = 0; i < 2; ++i) { const int key = i * 32 + (tid >> 4), ch = tid & 15;
;         pk[i] = *(const h16x8*)(proj + (size_t)(tb0 + key) * OD_N + 2048 + ch * 8);
;         pv[i] = *(const h16x8*)(proj + (size_t)(tb0 + key) * OD_N + 2176 + ch * 8); }
;     ATT_STAGE(0, 2048, 2176, 1);
;     unsigned long long mkn = bmq[0];
;     __syncthreads();
.LBB0_510:
	s_or_b64 exec, exec, s[4:5]
	v_add_u32_e32 v145, s84, v183
	v_and_b32_e32 v80, 31, v16
	v_add_u32_e32 v0, s58, v145
	v_bfe_u32 v81, v16, 5, 1
	v_or_b32_e32 v144, v80, v0
	v_mad_i64_i32 v[2:3], s[4:5], v144, s33, v[142:143]
	v_lshlrev_b32_e32 v0, 4, v81
	v_lshl_add_u64 v[34:35], v[2:3], 0, v[0:1]
	v_or_b32_e32 v0, v80, v145
	v_add_u32_e32 v14, s58, v0
	v_ashrrev_i32_e32 v17, 4, v16
	v_lshlrev_b32_e32 v0, 3, v16
	v_add_u32_e32 v147, s58, v17
	v_and_b32_e32 v0, 0x78, v0
	v_mov_b64_e32 v[36:37], s[14:15]
	v_mad_i64_i32 v[18:19], s[4:5], v147, s33, v[36:37]
	v_lshlrev_b32_e32 v0, 1, v0
	v_add_u32_e32 v22, 32, v147
	v_lshl_add_u64 v[18:19], v[18:19], 0, v[0:1]
	v_mad_i64_i32 v[22:23], s[4:5], v22, s33, v[36:37]
	v_add_co_u32_e32 v26, vcc, s3, v18
	s_min_i32 s4, s83, 1
	s_nop 0
	v_addc_co_u32_e32 v27, vcc, 0, v19, vcc
	v_lshl_add_u64 v[22:23], v[22:23], 0, v[0:1]
	v_lshl_add_u32 v40, s4, 6, v147
	v_add_co_u32_e32 v30, vcc, s3, v22
	v_mad_i64_i32 v[32:33], s[4:5], v40, s33, v[36:37]
	s_nop 0
	v_addc_co_u32_e32 v31, vcc, 0, v23, vcc
	v_lshl_add_u64 v[32:33], v[32:33], 0, v[0:1]
	v_add_u32_e32 v40, 32, v40
	v_add_co_u32_e32 v38, vcc, s3, v32
	v_mad_i64_i32 v[36:37], s[4:5], v40, s33, v[36:37]
	v_ashrrev_i32_e32 v15, 31, v14
	v_addc_co_u32_e32 v39, vcc, 0, v33, vcc
	v_lshl_add_u64 v[36:37], v[36:37], 0, v[0:1]
	global_load_dwordx4 v[2:5], v[34:35], off offset:3104
	global_load_dwordx4 v[6:9], v[34:35], off offset:3136
	global_load_dwordx4 v[10:13], v[34:35], off offset:3168
	global_load_dwordx4 v[96:99], v[34:35], off offset:3200
	global_load_dwordx4 v[100:103], v[34:35], off offset:3232
	global_load_dwordx4 v[104:107], v[34:35], off offset:3264
	v_lshlrev_b64 v[14:15], 9, v[14:15]
	global_load_dwordx4 v[108:111], v[34:35], off offset:3296
	global_load_dwordx4 v[18:21], v[26:27], off
	global_load_dwordx4 v[22:25], v[30:31], off
	s_nop 0
	global_load_dwordx4 v[26:29], v[26:27], off offset:256
	v_add_co_u32_e32 v36, vcc, 0x1000, v36
	v_lshl_add_u64 v[14:15], s[16:17], 0, v[14:15]
	global_load_dwordx4 v[30:33], v[30:31], off offset:256
	s_nop 0
	global_load_dwordx4 v[116:119], v[38:39], off
	v_addc_co_u32_e32 v37, vcc, 0, v37, vcc
	global_load_dwordx4 v[120:123], v[38:39], off offset:256
	global_load_dwordx4 v[128:131], v[36:37], off
	global_load_dwordx4 v[112:115], v[34:35], off offset:3072
	global_load_dwordx2 v[150:151], v[14:15], off
	global_load_dwordx4 v[124:127], v[36:37], off offset:256
	v_and_b32_e32 v16, 15, v16
	v_lshlrev_b32_e32 v34, 2, v16
	v_lshlrev_b32_e32 v35, 1, v17
	v_lshl_add_u32 v153, v16, 4, 0
	v_mul_u32_u24_e32 v155, 0x480, v16
	v_and_b32_e32 v16, 6, v35
	v_bfe_u32 v36, v17, 2, 1
	v_bfe_u32 v37, v17, 3, 1
	v_and_b32_e32 v38, -13, v17
	v_lshl_or_b32 v38, v36, 3, v38
	v_lshl_or_b32 v38, v37, 2, v38
	v_and_b32_e32 v34, 0x38, v34
	v_bitop3_b32 v36, v38, v34, -4 bitop3:0x6c
	v_mul_lo_u32 v154, v17, s97
	v_add_u32_e32 v162, 0, v16
	v_lshlrev_b32_e32 v163, 1, v36
	v_add_u32_e32 v35, v153, v154
	v_add3_u32 v16, v162, v163, v155
	s_mov_b64 s[4:5], -1
	s_cmp_gt_i32 s83, -1
	v_lshlrev_b32_e32 v152, 2, v81
	s_waitcnt vmcnt(9)
	ds_write_b128 v35, v[18:21]
	s_waitcnt vmcnt(7)
	ds_write_b16 v16, v26 offset:34816
	ds_write_b16_d16_hi v16, v26 offset:34960
	ds_write_b16 v16, v27 offset:35104
	ds_write_b16_d16_hi v16, v27 offset:35248
	ds_write_b16 v16, v28 offset:35392
	ds_write_b16_d16_hi v16, v28 offset:35536
	ds_write_b16 v16, v29 offset:35680
	ds_write_b16_d16_hi v16, v29 offset:35824
	v_add_u32_e32 v16, 32, v38
	v_bitop3_b32 v16, v16, v34, -4 bitop3:0x6c
	v_lshlrev_b32_e32 v164, 1, v16
	v_add3_u32 v16, v162, v164, v155
	ds_write_b128 v35, v[22:25] offset:8704
	s_waitcnt vmcnt(6)
	ds_write_b16 v16, v30 offset:34816
	ds_write_b16_d16_hi v16, v30 offset:34960
	ds_write_b16 v16, v31 offset:35104
	ds_write_b16_d16_hi v16, v31 offset:35248
	ds_write_b16 v16, v32 offset:35392
	ds_write_b16_d16_hi v16, v32 offset:35536
	ds_write_b16 v16, v33 offset:35680
	ds_write_b16_d16_hi v16, v33 offset:35824
	v_and_b32_e32 v240, 15, v80
	v_bfe_i32 v236, v240, 0, 1
	v_not_b32_e32 v236, v236
	v_and_b32_e32 v236, 0xff800000, v236
	v_bfe_i32 v237, v240, 1, 1
	v_not_b32_e32 v237, v237
	v_and_b32_e32 v237, 0xff800000, v237
	v_bfe_i32 v238, v240, 2, 1
	v_not_b32_e32 v238, v238
	v_and_b32_e32 v238, 0xff800000, v238
	v_bfe_i32 v239, v240, 3, 1
	v_not_b32_e32 v239, v239
	v_and_b32_e32 v239, 0xff800000, v239
	v_lshlrev_b32_e32 v240, 4, v240
	v_add_u32_e32 v240, 0x12400, v240
	ds_write_b128 v240, v[236:239]
	s_waitcnt lgkmcnt(0)
	s_barrier
	s_cbranch_scc0 .LBB0_591
	v_lshlrev_b32_e32 v146, 2, v81
	s_movk_i32 s4, 0x100
	v_lshlrev_b32_e64 v174, v146, s4
	s_movk_i32 s4, 0x200
	v_lshlrev_b32_e64 v175, v146, s4
	s_movk_i32 s4, 0x400
	v_lshlrev_b32_e64 v176, v146, s4
	s_movk_i32 s4, 0x800
	v_lshlrev_b32_e64 v177, v146, s4
	s_mov_b32 s4, 0x10000
	v_lshlrev_b32_e64 v178, v146, s4
	s_mov_b32 s4, 0x20000
	v_lshlrev_b32_e64 v179, v146, s4
	s_mov_b32 s4, 0x40000
	v_lshlrev_b32_e64 v180, v146, s4
	s_mov_b32 s4, 0x80000
	v_lshrrev_b32_e32 v16, 3, v80
	v_lshlrev_b32_e64 v181, v146, s4
	s_mov_b32 s4, 0x1000000
	v_xor_b32_e32 v16, v81, v16
	v_lshlrev_b32_e64 v192, v146, s4
	s_brev_b32 s4, 64
	v_lshlrev_b32_e32 v17, 2, v16
	v_lshrrev_b32_e32 v168, 4, v80
	v_xor_b32_e32 v168, v81, v168
	v_lshlrev_b32_e32 v168, 4, v168
	v_lshlrev_b32_e64 v193, v146, s4
	s_brev_b32 s4, 32
	v_add_u32_e32 v16, v145, v80
	v_mov_b32_e32 v30, v1
	v_mov_b32_e32 v31, v1
	v_xor_b32_e32 v165, 8, v17
	v_lshlrev_b32_e64 v194, v146, s4
	s_brev_b32 s4, 16
	v_sub_u32_e32 v196, v16, v146
	v_mov_b32_e32 v16, v1
	v_mov_b32_e32 v17, v1
	v_mov_b32_e32 v18, v1
	v_mov_b32_e32 v19, v1
	v_mov_b32_e32 v20, v1
	v_mov_b32_e32 v21, v1
	v_mov_b32_e32 v22, v1
	v_mov_b32_e32 v23, v1
	v_mov_b32_e32 v24, v1
	v_mov_b32_e32 v25, v1
	v_mov_b32_e32 v26, v1
	v_mov_b32_e32 v27, v1
	v_mov_b32_e32 v28, v1
	v_mov_b32_e32 v29, v1
	v_mov_b64_e32 v[46:47], v[30:31]
	v_mov_b64_e32 v[62:63], v[30:31]
	v_mov_b64_e32 v[78:79], v[30:31]
	s_mov_b32 s30, 2
	v_lshl_add_u32 v166, v81, 4, 0
	v_mad_u32_u24 v167, v80, s60, 0
	v_mul_u32_u24_e32 v169, 0x110, v80
	v_lshlrev_b32_e64 v170, v146, 1
	v_lshlrev_b32_e64 v171, v146, 2
	v_lshlrev_b32_e64 v172, v146, 4
	v_lshlrev_b32_e64 v173, v146, 8
	v_lshlrev_b32_e64 v195, v146, s4
	v_mov_b32_e32 v198, 0
	v_mov_b32_e32 v201, 0xff800000
	s_movk_i32 s31, 0xbf
	v_mov_b64_e32 v[44:45], v[28:29]
	v_mov_b64_e32 v[42:43], v[26:27]
	v_mov_b64_e32 v[40:41], v[24:25]
	v_mov_b64_e32 v[38:39], v[22:23]
	v_mov_b64_e32 v[36:37], v[20:21]
	v_mov_b64_e32 v[34:35], v[18:19]
	v_mov_b64_e32 v[32:33], v[16:17]
	v_mov_b64_e32 v[60:61], v[28:29]
	v_mov_b64_e32 v[58:59], v[26:27]
	v_mov_b64_e32 v[56:57], v[24:25]
	v_mov_b64_e32 v[54:55], v[22:23]
	v_mov_b64_e32 v[52:53], v[20:21]
	v_mov_b64_e32 v[50:51], v[18:19]
	v_mov_b64_e32 v[48:49], v[16:17]
	v_mov_b64_e32 v[76:77], v[28:29]
	v_mov_b64_e32 v[74:75], v[26:27]
	v_mov_b64_e32 v[72:73], v[24:25]
	v_mov_b64_e32 v[70:71], v[22:23]
	v_mov_b64_e32 v[68:69], v[20:21]
	v_mov_b64_e32 v[66:67], v[18:19]
	v_mov_b64_e32 v[64:65], v[16:17]

; #define LAS __attribute__((address_space(3)))
; __device__ __forceinline__ f32x16 mma32(const h16x8 a, const h16x8 b, const f32x16 c) { return __builtin_amdgcn_mfma_f32_32x32x16_f16(a, b, c, 0, 0, 0); }
; __device__ __forceinline__ void dsa_attn_item(CParams& p, LAS unsigned char* lds, int b, int qb, int tid_in, int wave) {
;     ...
;     for (int kt = 0; kt < nkt; ++kt) {
;         const int k0 = kt * 64; const int cur = kt & 1;
;         const LAS h16* Ks = Ks0 + cur * 8704; const LAS h16* Vt = Vt0 + cur * 9216;
;         const unsigned long long mk = mkn; mkn = bmq[kt + 1 < nkt ? kt + 1 : kt];
;         if (kt + 1 < nkt) ATT_STAGE(cur ^ 1, 2048, 2176, kt + 2);
;         if (__ballot(mk != 0ull) != 0ull) {
;             const bool far = (k0 + 63 + 128 <= q0);
;             const float bfar = bdh[128];
; #pragma unroll
;             for (int sub = 0; sub < 2; ++sub) {
;                 const unsigned mw = (unsigned)(mk >> (32 * sub));
;                 if (__ballot(mw != 0u) == 0ull) continue;
;                 f32x16 sc;
; #pragma unroll
;                 for (int i = 0; i < 16; ++i) sc[i] = 0.f;
; #pragma unroll
;                 for (int s = 0; s < 8; ++s) sc = mma32(*(const LAS h16x8*)(Ks + (32 * sub + r) * 136 + 16 * s + 8 * hh), qf[s], sc);
;                 float mx = -INFINITY;
; #pragma unroll
;                 for (int i = 0; i < 16; ++i) { const int ko = (i & 3) + 8 * (i >> 2) + 4 * hh; const int dist = qp - (k0 + 32 * sub + ko);
;                     float bias = bfar; if (!far) bias = bdh[dist < 0 ? 0 : (dist < 128 ? dist : 128)];
.LBB0_514:
	s_waitcnt vmcnt(2)
	v_cmp_ne_u64_e32 vcc, 0, v[150:151]
	s_cbranch_vccz .LBB0_588
	s_and_b32 s4, s34, 1
	s_mul_i32 s5, s4, 0x4400
	s_mulk_i32 s4, 0x4800
	v_add3_u32 v197, v166, v169, s5
	v_add3_u32 v199, v167, v168, s4
	v_readfirstlane_b32 s6, v145
	s_mov_b32 s7, 0x12400
	v_cmp_ne_u32_e32 vcc, 0, v150
	s_cbranch_vccz .LdsaA_s0_skip
	ds_read_b128 v[80:83], v197 offset:0
	ds_read_b128 v[84:87], v197 offset:32
	ds_read_b128 v[88:91], v197 offset:64
	ds_read_b128 v[92:95], v197 offset:96
	ds_read_b128 v[202:205], v197 offset:128
	ds_read_b128 v[206:209], v197 offset:160
	ds_read_b128 v[210:213], v197 offset:192
	ds_read_b128 v[228:231], v197 offset:224
	ds_read_b32 v200, v184 offset:512
	s_waitcnt lgkmcnt(5)
	v_mfma_f32_32x32x16_f16 v[236:251], v[80:83], v[112:115], 0
	v_mfma_f32_32x32x16_f16 v[236:251], v[84:87], v[2:5], v[236:251]
	v_mfma_f32_32x32x16_f16 v[236:251], v[88:91], v[6:9], v[236:251]
	v_mfma_f32_32x32x16_f16 v[236:251], v[92:95], v[10:13], v[236:251]
	s_waitcnt lgkmcnt(1)
	v_mfma_f32_32x32x16_f16 v[236:251], v[202:205], v[96:99], v[236:251]
	v_mfma_f32_32x32x16_f16 v[236:251], v[206:209], v[100:103], v[236:251]
	v_mfma_f32_32x32x16_f16 v[236:251], v[210:213], v[104:107], v[236:251]
	v_mfma_f32_32x32x16_f16 v[236:251], v[228:231], v[108:111], v[236:251]
	v_lshrrev_b32_e32 v214, v146, v150
	s_cmp_le_i32 s31, s6
	s_cbranch_scc1 .LdsaA_s0_far
	v_subrev_u32_e32 v202, 0, v196
	v_med3_i32 v202, v202, 0, v226
	v_lshl_add_u32 v202, v202, 2, v184
	ds_read_b32 v202, v202
	v_subrev_u32_e32 v203, 1, v196
	v_med3_i32 v203, v203, 0, v226
	v_lshl_add_u32 v203, v203, 2, v184
	ds_read_b32 v203, v203
	v_subrev_u32_e32 v204, 2, v196
	v_med3_i32 v204, v204, 0, v226
	v_lshl_add_u32 v204, v204, 2, v184
	ds_read_b32 v204, v204
	v_subrev_u32_e32 v205, 3, v196
	v_med3_i32 v205, v205, 0, v226
	v_lshl_add_u32 v205, v205, 2, v184
	ds_read_b32 v205, v205
	v_subrev_u32_e32 v206, 8, v196
	v_med3_i32 v206, v206, 0, v226
	v_lshl_add_u32 v206, v206, 2, v184
	ds_read_b32 v206, v206
	v_subrev_u32_e32 v207, 9, v196
	v_med3_i32 v207, v207, 0, v226
	v_lshl_add_u32 v207, v207, 2, v184
	ds_read_b32 v207, v207
	v_subrev_u32_e32 v208, 10, v196
	v_med3_i32 v208, v208, 0, v226
	v_lshl_add_u32 v208, v208, 2, v184
	ds_read_b32 v208, v208
	v_subrev_u32_e32 v209, 11, v196
	v_med3_i32 v209, v209, 0, v226
	v_lshl_add_u32 v209, v209, 2, v184
	ds_read_b32 v209, v209
	v_subrev_u32_e32 v210, 16, v196
	v_med3_i32 v210, v210, 0, v226
	v_lshl_add_u32 v210, v210, 2, v184
	ds_read_b32 v210, v210
	v_subrev_u32_e32 v211, 17, v196
	v_med3_i32 v211, v211, 0, v226
	v_lshl_add_u32 v211, v211, 2, v184
	ds_read_b32 v211, v211
	v_subrev_u32_e32 v212, 18, v196
	v_med3_i32 v212, v212, 0, v226
	v_lshl_add_u32 v212, v212, 2, v184
	ds_read_b32 v212, v212
	v_subrev_u32_e32 v213, 19, v196
	v_med3_i32 v213, v213, 0, v226
	v_lshl_add_u32 v213, v213, 2, v184
	ds_read_b32 v213, v213
	v_subrev_u32_e32 v80, 24, v196
	v_med3_i32 v80, v80, 0, v226
	v_lshl_add_u32 v80, v80, 2, v184
	ds_read_b32 v80, v80
	v_subrev_u32_e32 v81, 25, v196
	v_med3_i32 v81, v81, 0, v226
	v_lshl_add_u32 v81, v81, 2, v184
	ds_read_b32 v81, v81
	v_subrev_u32_e32 v82, 26, v196
	v_med3_i32 v82, v82, 0, v226
	v_lshl_add_u32 v82, v82, 2, v184
	ds_read_b32 v82, v82
	v_subrev_u32_e32 v83, 27, v196
	v_med3_i32 v83, v83, 0, v226
	v_lshl_add_u32 v83, v83, 2, v184
	ds_read_b32 v83, v83
	s_waitcnt lgkmcnt(0)
	s_nop 2
	v_add_f32_e32 v236, v236, v202
	v_add_f32_e32 v237, v237, v203
	v_add_f32_e32 v238, v238, v204
	v_add_f32_e32 v239, v239, v205
	v_add_f32_e32 v240, v240, v206
	v_add_f32_e32 v241, v241, v207
	v_add_f32_e32 v242, v242, v208
	v_add_f32_e32 v243, v243, v209
	v_add_f32_e32 v244, v244, v210
	v_add_f32_e32 v245, v245, v211
	v_add_f32_e32 v246, v246, v212
	v_add_f32_e32 v247, v247, v213
	v_add_f32_e32 v248, v248, v80
	v_add_f32_e32 v249, v249, v81
	v_add_f32_e32 v250, v250, v82
	v_add_f32_e32 v251, v251, v83
	v_mov_b32_e32 v200, 0
; #define LAS __attribute__((address_space(3)))
; __device__ __forceinline__ f32x16 mma32(const h16x8 a, const h16x8 b, const f32x16 c) { return __builtin_amdgcn_mfma_f32_32x32x16_f16(a, b, c, 0, 0, 0); }
; __device__ __forceinline__ void dsa_attn_item(CParams& p, LAS unsigned char* lds, int b, int qb, int tid_in, int wave) {
;     ...
;                 float mx = -INFINITY;
; #pragma unroll
;                 for (int i = 0; i < 16; ++i) { const int ko = (i & 3) + 8 * (i >> 2) + 4 * hh; const int dist = qp - (k0 + 32 * sub + ko);
;                     float bias = bfar; if (!far) bias = bdh[dist < 0 ? 0 : (dist < 128 ? dist : 128)];
;                     const float v = ((mw >> ko) & 1u) ? sc[i] + bias : -INFINITY; sc[i] = v; mx = fmaxf(mx, v); }
;                 mx = fmaxf(mx, __shfl_xor(mx, 32));
;                 const float m_new = fmaxf(m_run, mx);
;                 const float msafe = (m_new == -INFINITY) ? 0.f : m_new;
;                 const float alpha = __builtin_amdgcn_exp2f(m_run - msafe);
;                 const bool resc = __ballot(m_new > m_run) != 0ull;
;                 float ls = 0.f;
; #pragma unroll
;                 for (int i = 0; i < 16; ++i) { const float e = __builtin_amdgcn_exp2f(sc[i] - msafe); sc[i] = e; ls += e; }
;                 ls += __shfl_xor(ls, 32);
;                 l_run = l_run * alpha + ls; m_run = m_new;
;                 if (resc) {
; #pragma unroll
;                     for (int d = 0; d < 4; ++d)
; #pragma unroll
;                         for (int i = 0; i < 16; ++i) o[d][i] *= alpha;
;                 }
; #pragma unroll
;                 for (int s2 = 0; s2 < 2; ++s2) {
;                     h16x8 pf;
; #pragma unroll
;                     for (int jj = 0; jj < 8; ++jj) pf[jj] = (h16)sc[8 * s2 + jj];
; #pragma unroll
;                     for (int d = 0; d < 4; ++d) {
;                         const int coff = 32 * d * 72 + ((((sub << 1) | s2) ^ d) << 4);
;                         const h16x4 lo = *(const LAS h16x4*)(Vt + vlo + coff), hi = *(const LAS h16x4*)(Vt + vhi + coff);
;                         h16x8 vf; vf[0] = lo[0]; vf[1] = lo[1]; vf[2] = lo[2]; vf[3] = lo[3]; vf[4] = hi[0]; vf[5] = hi[1]; vf[6] = hi[2]; vf[7] = hi[3];
;                         o[d] = mma32(vf, pf, o[d]);
;                     }
.LdsaA_s0_far:
	v_bfe_u32 v84, v214, 0, 4
	v_bfe_u32 v85, v214, 8, 4
	v_bfe_u32 v86, v214, 16, 4
	v_bfe_u32 v87, v214, 24, 4
	v_lshl_add_u32 v84, v84, 4, s7
	v_lshl_add_u32 v85, v85, 4, s7
	v_lshl_add_u32 v86, v86, 4, s7
	v_lshl_add_u32 v87, v87, 4, s7
	ds_read_b128 v[202:205], v84
	ds_read_b128 v[206:209], v85
	ds_read_b128 v[210:213], v86
	ds_read_b128 v[80:83], v87
	s_waitcnt lgkmcnt(0)
	v_pk_add_f32 v[236:237], v[236:237], v[202:203]
	v_pk_add_f32 v[238:239], v[238:239], v[204:205]
	v_pk_add_f32 v[240:241], v[240:241], v[206:207]
	v_pk_add_f32 v[242:243], v[242:243], v[208:209]
	v_pk_add_f32 v[244:245], v[244:245], v[210:211]
	v_pk_add_f32 v[246:247], v[246:247], v[212:213]
	v_pk_add_f32 v[248:249], v[248:249], v[80:81]
	v_pk_add_f32 v[250:251], v[250:251], v[82:83]
	v_max3_f32 v84, v236, v237, v238
	v_max3_f32 v84, v84, v239, v240
	v_max3_f32 v84, v84, v241, v242
	v_max3_f32 v84, v84, v243, v244
	v_max3_f32 v84, v84, v245, v246
	v_max3_f32 v84, v84, v247, v248
	v_max3_f32 v84, v84, v249, v250
	v_max_f32_e32 v84, v84, v251
	s_waitcnt lgkmcnt(0)
	v_add_f32_e32 v84, v84, v200
	ds_bpermute_b32 v215, v185, v84
	s_waitcnt lgkmcnt(0)
	v_max3_f32 v85, v201, v84, v215
	v_cmp_neq_f32_e32 vcc, s78, v85
	s_nop 1
	v_cndmask_b32_e32 v86, 0, v85, vcc
	v_sub_f32_e32 v88, v201, v86
	v_exp_f32_e32 v88, v88
	v_cmp_gt_f32_e32 vcc, v85, v201
	v_sub_f32_e32 v90, v86, v200
	v_mov_b32_e32 v201, v85
	v_pk_add_f32 v[236:237], v[236:237], v[90:91] op_sel_hi:[1,0] neg_lo:[0,1] neg_hi:[0,1]
	v_pk_add_f32 v[238:239], v[238:239], v[90:91] op_sel_hi:[1,0] neg_lo:[0,1] neg_hi:[0,1]
	v_pk_add_f32 v[240:241], v[240:241], v[90:91] op_sel_hi:[1,0] neg_lo:[0,1] neg_hi:[0,1]
	v_pk_add_f32 v[242:243], v[242:243], v[90:91] op_sel_hi:[1,0] neg_lo:[0,1] neg_hi:[0,1]
	v_pk_add_f32 v[244:245], v[244:245], v[90:91] op_sel_hi:[1,0] neg_lo:[0,1] neg_hi:[0,1]
	v_pk_add_f32 v[246:247], v[246:247], v[90:91] op_sel_hi:[1,0] neg_lo:[0,1] neg_hi:[0,1]
	v_pk_add_f32 v[248:249], v[248:249], v[90:91] op_sel_hi:[1,0] neg_lo:[0,1] neg_hi:[0,1]
	v_pk_add_f32 v[250:251], v[250:251], v[90:91] op_sel_hi:[1,0] neg_lo:[0,1] neg_hi:[0,1]
	v_exp_f32_e32 v236, v236
	v_exp_f32_e32 v237, v237
	v_exp_f32_e32 v238, v238
	v_exp_f32_e32 v239, v239
	v_exp_f32_e32 v240, v240
	v_exp_f32_e32 v241, v241
	v_exp_f32_e32 v242, v242
	v_exp_f32_e32 v243, v243
	v_exp_f32_e32 v244, v244
	v_exp_f32_e32 v245, v245
	v_exp_f32_e32 v246, v246
	v_exp_f32_e32 v247, v247
	v_exp_f32_e32 v248, v248
	v_exp_f32_e32 v249, v249
	v_exp_f32_e32 v250, v250
	v_exp_f32_e32 v251, v251
	v_pk_add_f32 v[92:93], v[236:237], v[238:239]
	v_pk_add_f32 v[92:93], v[92:93], v[240:241]
	v_pk_add_f32 v[92:93], v[92:93], v[242:243]
	v_pk_add_f32 v[92:93], v[92:93], v[244:245]
	v_pk_add_f32 v[92:93], v[92:93], v[246:247]
	v_pk_add_f32 v[92:93], v[92:93], v[248:249]
	v_pk_add_f32 v[92:93], v[92:93], v[250:251]
	s_nop 0
	v_add_f32_e32 v92, v92, v93
	ds_bpermute_b32 v215, v185, v92
	v_cvt_pk_f16_f32 v232, v236, v237
	v_cvt_pk_f16_f32 v233, v238, v239
	v_cvt_pk_f16_f32 v234, v240, v241
	v_cvt_pk_f16_f32 v235, v242, v243
	v_cvt_pk_f16_f32 v228, v244, v245
	v_cvt_pk_f16_f32 v229, v246, v247
	v_cvt_pk_f16_f32 v230, v248, v249
	v_cvt_pk_f16_f32 v231, v250, v251
	s_waitcnt lgkmcnt(0)
	v_add_f32_e32 v92, v92, v215
	v_fma_f32 v198, v198, v88, v92
	ds_read_b128 v[236:239], v199 offset:34848
	ds_read_b128 v[240:243], v199 offset:39424
	ds_read_b128 v[244:247], v199 offset:44128
	ds_read_b128 v[248:251], v199 offset:48704
	s_cbranch_vccz .LdsaA_s0_noresc
	v_pk_mul_f32 v[64:65], v[64:65], v[88:89] op_sel_hi:[1,0]
	v_pk_mul_f32 v[66:67], v[66:67], v[88:89] op_sel_hi:[1,0]
	v_pk_mul_f32 v[68:69], v[68:69], v[88:89] op_sel_hi:[1,0]
	v_pk_mul_f32 v[70:71], v[70:71], v[88:89] op_sel_hi:[1,0]
	v_pk_mul_f32 v[72:73], v[72:73], v[88:89] op_sel_hi:[1,0]
	v_pk_mul_f32 v[74:75], v[74:75], v[88:89] op_sel_hi:[1,0]
	v_pk_mul_f32 v[76:77], v[76:77], v[88:89] op_sel_hi:[1,0]
	v_pk_mul_f32 v[78:79], v[78:79], v[88:89] op_sel_hi:[1,0]
	v_pk_mul_f32 v[48:49], v[48:49], v[88:89] op_sel_hi:[1,0]
	v_pk_mul_f32 v[50:51], v[50:51], v[88:89] op_sel_hi:[1,0]
	v_pk_mul_f32 v[52:53], v[52:53], v[88:89] op_sel_hi:[1,0]
	v_pk_mul_f32 v[54:55], v[54:55], v[88:89] op_sel_hi:[1,0]
	v_pk_mul_f32 v[56:57], v[56:57], v[88:89] op_sel_hi:[1,0]
	v_pk_mul_f32 v[58:59], v[58:59], v[88:89] op_sel_hi:[1,0]
	v_pk_mul_f32 v[60:61], v[60:61], v[88:89] op_sel_hi:[1,0]
	v_pk_mul_f32 v[62:63], v[62:63], v[88:89] op_sel_hi:[1,0]
	v_pk_mul_f32 v[32:33], v[32:33], v[88:89] op_sel_hi:[1,0]
	v_pk_mul_f32 v[34:35], v[34:35], v[88:89] op_sel_hi:[1,0]
	v_pk_mul_f32 v[36:37], v[36:37], v[88:89] op_sel_hi:[1,0]
	v_pk_mul_f32 v[38:39], v[38:39], v[88:89] op_sel_hi:[1,0]
	v_pk_mul_f32 v[40:41], v[40:41], v[88:89] op_sel_hi:[1,0]
	v_pk_mul_f32 v[42:43], v[42:43], v[88:89] op_sel_hi:[1,0]
	v_pk_mul_f32 v[44:45], v[44:45], v[88:89] op_sel_hi:[1,0]
	v_pk_mul_f32 v[46:47], v[46:47], v[88:89] op_sel_hi:[1,0]
	v_pk_mul_f32 v[16:17], v[16:17], v[88:89] op_sel_hi:[1,0]
	v_pk_mul_f32 v[18:19], v[18:19], v[88:89] op_sel_hi:[1,0]
	v_pk_mul_f32 v[20:21], v[20:21], v[88:89] op_sel_hi:[1,0]
	v_pk_mul_f32 v[22:23], v[22:23], v[88:89] op_sel_hi:[1,0]
	v_pk_mul_f32 v[24:25], v[24:25], v[88:89] op_sel_hi:[1,0]
	v_pk_mul_f32 v[26:27], v[26:27], v[88:89] op_sel_hi:[1,0]
	v_pk_mul_f32 v[28:29], v[28:29], v[88:89] op_sel_hi:[1,0]
	v_pk_mul_f32 v[30:31], v[30:31], v[88:89] op_sel_hi:[1,0]

; #define LAS __attribute__((address_space(3)))
; __device__ __forceinline__ f32x16 mma32(const h16x8 a, const h16x8 b, const f32x16 c) { return __builtin_amdgcn_mfma_f32_32x32x16_f16(a, b, c, 0, 0, 0); }
; __device__ __forceinline__ void dsa_attn_item(CParams& p, LAS unsigned char* lds, int b, int qb, int tid_in, int wave) {
;     ...
;                 float mx = -INFINITY;
; #pragma unroll
;                 for (int i = 0; i < 16; ++i) { const int ko = (i & 3) + 8 * (i >> 2) + 4 * hh; const int dist = qp - (k0 + 32 * sub + ko);
;                     float bias = bfar; if (!far) bias = bdh[dist < 0 ? 0 : (dist < 128 ? dist : 128)];
;                     const float v = ((mw >> ko) & 1u) ? sc[i] + bias : -INFINITY; sc[i] = v; mx = fmaxf(mx, v); }
;                 mx = fmaxf(mx, __shfl_xor(mx, 32));
;                 const float m_new = fmaxf(m_run, mx);
;                 const float msafe = (m_new == -INFINITY) ? 0.f : m_new;
;                 const float alpha = __builtin_amdgcn_exp2f(m_run - msafe);
;                 const bool resc = __ballot(m_new > m_run) != 0ull;
;                 float ls = 0.f;
; #pragma unroll
;                 for (int i = 0; i < 16; ++i) { const float e = __builtin_amdgcn_exp2f(sc[i] - msafe); sc[i] = e; ls += e; }
;                 ls += __shfl_xor(ls, 32);
;                 l_run = l_run * alpha + ls; m_run = m_new;
;                 if (resc) {
; #pragma unroll
;                     for (int d = 0; d < 4; ++d)
; #pragma unroll
;                         for (int i = 0; i < 16; ++i) o[d][i] *= alpha;
;                 }
; #pragma unroll
;                 for (int s2 = 0; s2 < 2; ++s2) {
;                     h16x8 pf;
; #pragma unroll
;                     for (int jj = 0; jj < 8; ++jj) pf[jj] = (h16)sc[8 * s2 + jj];
; #pragma unroll
;                     for (int d = 0; d < 4; ++d) {
;                         const int coff = 32 * d * 72 + ((((sub << 1) | s2) ^ d) << 4);
;                         const h16x4 lo = *(const LAS h16x4*)(Vt + vlo + coff), hi = *(const LAS h16x4*)(Vt + vhi + coff);
;                         h16x8 vf; vf[0] = lo[0]; vf[1] = lo[1]; vf[2] = lo[2]; vf[3] = lo[3]; vf[4] = hi[0]; vf[5] = hi[1]; vf[6] = hi[2]; vf[7] = hi[3];
;                         o[d] = mma32(vf, pf, o[d]);
;                     }
.LdsaA_s1_far:
	v_bfe_u32 v84, v214, 0, 4
	v_bfe_u32 v85, v214, 8, 4
	v_bfe_u32 v86, v214, 16, 4
	v_bfe_u32 v87, v214, 24, 4
	v_lshl_add_u32 v84, v84, 4, s7
	v_lshl_add_u32 v85, v85, 4, s7
	v_lshl_add_u32 v86, v86, 4, s7
	v_lshl_add_u32 v87, v87, 4, s7
	ds_read_b128 v[202:205], v84
	ds_read_b128 v[206:209], v85
	ds_read_b128 v[210:213], v86
	ds_read_b128 v[80:83], v87
	s_waitcnt lgkmcnt(0)
	v_pk_add_f32 v[236:237], v[236:237], v[202:203]
	v_pk_add_f32 v[238:239], v[238:239], v[204:205]
	v_pk_add_f32 v[240:241], v[240:241], v[206:207]
	v_pk_add_f32 v[242:243], v[242:243], v[208:209]
	v_pk_add_f32 v[244:245], v[244:245], v[210:211]
	v_pk_add_f32 v[246:247], v[246:247], v[212:213]
	v_pk_add_f32 v[248:249], v[248:249], v[80:81]
	v_pk_add_f32 v[250:251], v[250:251], v[82:83]
	v_max3_f32 v84, v236, v237, v238
	v_max3_f32 v84, v84, v239, v240
	v_max3_f32 v84, v84, v241, v242
	v_max3_f32 v84, v84, v243, v244
	v_max3_f32 v84, v84, v245, v246
	v_max3_f32 v84, v84, v247, v248
	v_max3_f32 v84, v84, v249, v250
	v_max_f32_e32 v84, v84, v251
	s_waitcnt lgkmcnt(0)
	v_add_f32_e32 v84, v84, v200
	ds_bpermute_b32 v215, v185, v84
	s_waitcnt lgkmcnt(0)
	v_max3_f32 v85, v201, v84, v215
	v_cmp_neq_f32_e32 vcc, s78, v85
	s_nop 1
	v_cndmask_b32_e32 v86, 0, v85, vcc
	v_sub_f32_e32 v88, v201, v86
	v_exp_f32_e32 v88, v88
	v_cmp_gt_f32_e32 vcc, v85, v201
	v_sub_f32_e32 v90, v86, v200
	v_mov_b32_e32 v201, v85
	v_pk_add_f32 v[236:237], v[236:237], v[90:91] op_sel_hi:[1,0] neg_lo:[0,1] neg_hi:[0,1]
	v_pk_add_f32 v[238:239], v[238:239], v[90:91] op_sel_hi:[1,0] neg_lo:[0,1] neg_hi:[0,1]
	v_pk_add_f32 v[240:241], v[240:241], v[90:91] op_sel_hi:[1,0] neg_lo:[0,1] neg_hi:[0,1]
	v_pk_add_f32 v[242:243], v[242:243], v[90:91] op_sel_hi:[1,0] neg_lo:[0,1] neg_hi:[0,1]
	v_pk_add_f32 v[244:245], v[244:245], v[90:91] op_sel_hi:[1,0] neg_lo:[0,1] neg_hi:[0,1]
	v_pk_add_f32 v[246:247], v[246:247], v[90:91] op_sel_hi:[1,0] neg_lo:[0,1] neg_hi:[0,1]
	v_pk_add_f32 v[248:249], v[248:249], v[90:91] op_sel_hi:[1,0] neg_lo:[0,1] neg_hi:[0,1]
	v_pk_add_f32 v[250:251], v[250:251], v[90:91] op_sel_hi:[1,0] neg_lo:[0,1] neg_hi:[0,1]
	v_exp_f32_e32 v236, v236
	v_exp_f32_e32 v237, v237
	v_exp_f32_e32 v238, v238
	v_exp_f32_e32 v239, v239
	v_exp_f32_e32 v240, v240
	v_exp_f32_e32 v241, v241
	v_exp_f32_e32 v242, v242
	v_exp_f32_e32 v243, v243
	v_exp_f32_e32 v244, v244
	v_exp_f32_e32 v245, v245
	v_exp_f32_e32 v246, v246
	v_exp_f32_e32 v247, v247
	v_exp_f32_e32 v248, v248
	v_exp_f32_e32 v249, v249
	v_exp_f32_e32 v250, v250
	v_exp_f32_e32 v251, v251
	v_pk_add_f32 v[92:93], v[236:237], v[238:239]
	v_pk_add_f32 v[92:93], v[92:93], v[240:241]
	v_pk_add_f32 v[92:93], v[92:93], v[242:243]
	v_pk_add_f32 v[92:93], v[92:93], v[244:245]
	v_pk_add_f32 v[92:93], v[92:93], v[246:247]
	v_pk_add_f32 v[92:93], v[92:93], v[248:249]
	v_pk_add_f32 v[92:93], v[92:93], v[250:251]
	s_nop 0
	v_add_f32_e32 v92, v92, v93
	ds_bpermute_b32 v215, v185, v92
	v_cvt_pk_f16_f32 v232, v236, v237
	v_cvt_pk_f16_f32 v233, v238, v239
	v_cvt_pk_f16_f32 v234, v240, v241
	v_cvt_pk_f16_f32 v235, v242, v243
	v_cvt_pk_f16_f32 v228, v244, v245
	v_cvt_pk_f16_f32 v229, v246, v247
	v_cvt_pk_f16_f32 v230, v248, v249
	v_cvt_pk_f16_f32 v231, v250, v251
	s_waitcnt lgkmcnt(0)
	v_add_f32_e32 v92, v92, v215
	v_fma_f32 v198, v198, v88, v92
	ds_read_b128 v[236:239], v199 offset:34912
	ds_read_b128 v[240:243], v199 offset:39488
	ds_read_b128 v[244:247], v199 offset:44064
	ds_read_b128 v[248:251], v199 offset:48640
	s_cbranch_vccz .LdsaA_s1_noresc
	v_pk_mul_f32 v[64:65], v[64:65], v[88:89] op_sel_hi:[1,0]
	v_pk_mul_f32 v[66:67], v[66:67], v[88:89] op_sel_hi:[1,0]
	v_pk_mul_f32 v[68:69], v[68:69], v[88:89] op_sel_hi:[1,0]
	v_pk_mul_f32 v[70:71], v[70:71], v[88:89] op_sel_hi:[1,0]
	v_pk_mul_f32 v[72:73], v[72:73], v[88:89] op_sel_hi:[1,0]
	v_pk_mul_f32 v[74:75], v[74:75], v[88:89] op_sel_hi:[1,0]
	v_pk_mul_f32 v[76:77], v[76:77], v[88:89] op_sel_hi:[1,0]
	v_pk_mul_f32 v[78:79], v[78:79], v[88:89] op_sel_hi:[1,0]
	v_pk_mul_f32 v[48:49], v[48:49], v[88:89] op_sel_hi:[1,0]
	v_pk_mul_f32 v[50:51], v[50:51], v[88:89] op_sel_hi:[1,0]
	v_pk_mul_f32 v[52:53], v[52:53], v[88:89] op_sel_hi:[1,0]
	v_pk_mul_f32 v[54:55], v[54:55], v[88:89] op_sel_hi:[1,0]
	v_pk_mul_f32 v[56:57], v[56:57], v[88:89] op_sel_hi:[1,0]
	v_pk_mul_f32 v[58:59], v[58:59], v[88:89] op_sel_hi:[1,0]
	v_pk_mul_f32 v[60:61], v[60:61], v[88:89] op_sel_hi:[1,0]
	v_pk_mul_f32 v[62:63], v[62:63], v[88:89] op_sel_hi:[1,0]
	v_pk_mul_f32 v[32:33], v[32:33], v[88:89] op_sel_hi:[1,0]
	v_pk_mul_f32 v[34:35], v[34:35], v[88:89] op_sel_hi:[1,0]
	v_pk_mul_f32 v[36:37], v[36:37], v[88:89] op_sel_hi:[1,0]
	v_pk_mul_f32 v[38:39], v[38:39], v[88:89] op_sel_hi:[1,0]
	v_pk_mul_f32 v[40:41], v[40:41], v[88:89] op_sel_hi:[1,0]
	v_pk_mul_f32 v[42:43], v[42:43], v[88:89] op_sel_hi:[1,0]
	v_pk_mul_f32 v[44:45], v[44:45], v[88:89] op_sel_hi:[1,0]
	v_pk_mul_f32 v[46:47], v[46:47], v[88:89] op_sel_hi:[1,0]
	v_pk_mul_f32 v[16:17], v[16:17], v[88:89] op_sel_hi:[1,0]
	v_pk_mul_f32 v[18:19], v[18:19], v[88:89] op_sel_hi:[1,0]
	v_pk_mul_f32 v[20:21], v[20:21], v[88:89] op_sel_hi:[1,0]
	v_pk_mul_f32 v[22:23], v[22:23], v[88:89] op_sel_hi:[1,0]
	v_pk_mul_f32 v[24:25], v[24:25], v[88:89] op_sel_hi:[1,0]
	v_pk_mul_f32 v[26:27], v[26:27], v[88:89] op_sel_hi:[1,0]
	v_pk_mul_f32 v[28:29], v[28:29], v[88:89] op_sel_hi:[1,0]
	v_pk_mul_f32 v[30:31], v[30:31], v[88:89] op_sel_hi:[1,0]

; #define LAS __attribute__((address_space(3)))
;     __device__ __forceinline__ void operator()(const f32x4 (&acc_c)[2][2][4][2], const Unit& u, int wr, int wc, int fr, int fq) const {
;     ...
;         asm volatile("s_waitcnt lgkmcnt(0)" ::: "memory");
;         __builtin_amdgcn_s_barrier(); __builtin_amdgcn_s_barrier();
;         asm volatile("" ::: "memory");
; #pragma unroll
;         for (int n = 0; n < 2; ++n) {
;             f32x4 wg[3], wv[3], bg, bv;
; #pragma unroll
;             for (int t = 0; t < 3; ++t) { wg[t] = *(const f32x4*)(cw + t * FF2 + ch0 + 4 * n); wv[t] = *(const f32x4*)(cw + t * FF2 + FF + ch0 + 4 * n); }
;             bg = *(const f32x4*)(cb + ch0 + 4 * n); bv = *(const f32x4*)(cb + FF + ch0 + 4 * n);
; #pragma unroll
;             for (int ai = 0; ai < 2; ++ai) {
;                 f32x4 xpg = {0.f, 0.f, 0.f, 0.f}, xpv = {0.f, 0.f, 0.f, 0.f};
;                 const bool top = (ai == 0 && wr == 0);
;                 if (!top && fr >= 14) { const int ps = (wr == 1) ? ((ai * 2) * 4 + wc) : (((ai - 1) * 2 + 1) * 4 + wc);
;                     xpg = *(const LAS f32x4*)(xch + ps * 128 + (fr - 14) * 64 + 8 * fq + 4 * n); xpv = *(const LAS f32x4*)(xch + ps * 128 + (fr - 14) * 64 + 32 + 8 * fq + 4 * n); }
.LBB0_1440:
	s_or_b64 exec, exec, s[48:49]
	v_lshl_or_b32 v214, s72, 7, v170
	v_ashrrev_i32_e32 v215, 31, v214
	v_lshlrev_b64 v[102:103], 2, v[214:215]
	s_waitcnt lgkmcnt(0)
	s_barrier
	v_lshl_add_u64 v[186:187], s[16:17], 0, v[102:103]
	v_lshl_add_u64 v[90:91], s[26:27], 0, v[102:103]
	v_lshl_add_u64 v[94:95], s[28:29], 0, v[102:103]
	global_load_dwordx4 v[106:109], v[186:187], off
	s_nop 0
	global_load_dwordx4 v[90:93], v[90:91], off
	s_nop 0
	global_load_dwordx4 v[110:113], v[94:95], off
	v_lshl_add_u64 v[94:95], s[30:31], 0, v[102:103]
	v_lshl_add_u64 v[98:99], s[34:35], 0, v[102:103]
	global_load_dwordx4 v[94:97], v[94:95], off
	s_nop 0
	global_load_dwordx4 v[114:117], v[98:99], off
	v_lshl_add_u64 v[98:99], s[36:37], 0, v[102:103]
	v_lshl_add_u64 v[188:189], s[18:19], 0, v[102:103]
	v_lshl_add_u64 v[102:103], s[38:39], 0, v[102:103]
	global_load_dwordx4 v[98:101], v[98:99], off
	v_mov_b32_e32 v146, 0
	global_load_dwordx4 v[118:121], v[188:189], off
	v_mov_b32_e32 v152, 0
	global_load_dwordx4 v[102:105], v[102:103], off
	v_mov_b32_e32 v153, 0
	v_mov_b32_e32 v154, 0
	v_mov_b32_e32 v155, 0
	v_mov_b32_e32 v148, 0
	v_mov_b32_e32 v149, 0
	v_mov_b32_e32 v150, 0
	v_mov_b32_e32 v151, 0
	s_and_saveexec_b64 s[4:5], s[22:23]
	s_cbranch_execz .LBB0_1442
	ds_read_b128 v[152:155], v233
	ds_read_b128 v[148:151], v232
